# P0 H-row split 13/19 -> 11/21 between table-building and streaming workgroups; P5 epilogue preloads its 8 row scales from LDS once
# speedup vs baseline: 1.0050x; 1.0050x over previous
.LBB0_152:
.LBB0_153:
	s_and_b64 s[8:9], s[8:9], exec
	s_cselect_b32 s14, 11, 21
.LBB0_154:
	s_andn2_b64 vcc, exec, s[10:11]
	s_mov_b32 s8, s39
	s_cbranch_vccnz .LBB0_160
	s_and_b64 vcc, exec, s[6:7]
	s_cbranch_vccz .LBB0_157
	s_add_i32 s6, s63, s3
	s_add_i32 s8, s6, 0x2800
	s_cbranch_execz .LBB0_158
	s_branch .LBB0_159

.LBB0_875:
	v_lshl_add_u32 v150, s71, 10, v148
	ds_read_b32 v241, v150
	ds_read_b32 v242, v150 offset:64
	ds_read_b32 v243, v150 offset:128
	ds_read_b32 v244, v150 offset:192
	ds_read_b32 v245, v150 offset:512
	ds_read_b32 v246, v150 offset:576
	ds_read_b32 v247, v150 offset:640
	ds_read_b32 v248, v150 offset:704
	s_lshl_b32 s23, s59, 7
	s_or_b32 s23, s23, s67
	s_ashr_i32 s28, s23, 6
	s_lshl_b32 s21, s14, 8
	s_waitcnt lgkmcnt(0)
	v_mul_f32_e32 v154, 0xbfb8aa3b, v241
	v_pk_mul_f32 v[156:157], v[80:81], v[154:155] op_sel_hi:[1,0]
	v_pk_mul_f32 v[158:159], v[78:79], v[154:155] op_sel_hi:[1,0]
	v_exp_f32_e32 v156, v156
	v_exp_f32_e32 v158, v158
	v_exp_f32_e32 v157, v157
	v_exp_f32_e32 v159, v159
	v_pk_mul_f32 v[80:81], v[100:101], v[80:81]
	v_pk_mul_f32 v[78:79], v[98:99], v[78:79]
	v_pk_add_f32 v[98:99], v[156:157], 1.0 op_sel_hi:[1,0]
	v_pk_add_f32 v[100:101], v[158:159], 1.0 op_sel_hi:[1,0]
	v_rcp_f32_e32 v98, v98
	v_rcp_f32_e32 v100, v100
	v_rcp_f32_e32 v99, v99
	v_rcp_f32_e32 v101, v101
	v_mul_f32_e32 v152, v241, v241
	v_pk_mul_f32 v[80:81], v[80:81], v[152:153] op_sel_hi:[1,0]
	v_pk_mul_f32 v[78:79], v[78:79], v[152:153] op_sel_hi:[1,0]
	v_pk_mul_f32 v[80:81], v[80:81], v[98:99]
	v_pk_mul_f32 v[78:79], v[78:79], v[100:101]
	v_pk_mul_f32 v[98:99], v[16:17], v[154:155] op_sel_hi:[1,0]
	v_pk_mul_f32 v[100:101], v[14:15], v[154:155] op_sel_hi:[1,0]
	v_exp_f32_e32 v98, v98
	v_exp_f32_e32 v100, v100
	v_exp_f32_e32 v99, v99
	v_exp_f32_e32 v101, v101
	v_pk_mul_f32 v[16:17], v[36:37], v[16:17]
	v_pk_mul_f32 v[14:15], v[34:35], v[14:15]
	v_pk_add_f32 v[34:35], v[98:99], 1.0 op_sel_hi:[1,0]
	v_pk_add_f32 v[36:37], v[100:101], 1.0 op_sel_hi:[1,0]
	v_rcp_f32_e32 v34, v34
	v_rcp_f32_e32 v36, v36
	v_rcp_f32_e32 v35, v35
	v_rcp_f32_e32 v37, v37
	s_ashr_i32 s29, s28, 31
	v_pk_mul_f32 v[16:17], v[16:17], v[152:153] op_sel_hi:[1,0]
	v_pk_mul_f32 v[14:15], v[14:15], v[152:153] op_sel_hi:[1,0]
	s_lshl_b64 s[28:29], s[28:29], 22
	v_pk_mul_f32 v[34:35], v[16:17], v[34:35]
	v_pk_mul_f32 v[16:17], v[14:15], v[36:37]
	v_add_u32_e32 v36, s21, v1
	v_ashrrev_i32_e32 v37, 31, v36
	s_add_u32 s28, s64, s28
	v_cvt_pk_bf16_f32 v14, v78, v79
	v_cvt_pk_bf16_f32 v15, v80, v81
	v_cvt_pk_bf16_f32 v16, v16, v17
	v_cvt_pk_bf16_f32 v17, v34, v35
	s_addc_u32 s29, s65, s29
	v_lshlrev_b64 v[34:35], 7, v[36:37]
	v_lshl_add_u64 v[34:35], s[28:29], 0, v[34:35]
	v_lshl_add_u64 v[34:35], v[34:35], 0, v[130:131]
	global_store_dwordx4 v[34:35], v[14:17], off
	v_mov_b32_e32 v151, s75
	ds_read_b128 v[78:81], v151
	ds_read_b128 v[14:17], v151
	ds_read_b128 v[98:101], v151
	ds_read_b128 v[34:37], v151
	s_andn2_b64 vcc, exec, s[6:7]
	v_mul_f32_e32 v154, 0xbfb8aa3b, v242
	v_pk_mul_f32 v[156:157], v[68:69], v[154:155] op_sel_hi:[1,0]
	v_pk_mul_f32 v[158:159], v[66:67], v[154:155] op_sel_hi:[1,0]
	v_exp_f32_e32 v156, v156
	v_exp_f32_e32 v158, v158
	v_exp_f32_e32 v157, v157
	v_exp_f32_e32 v159, v159
	v_pk_mul_f32 v[68:69], v[84:85], v[68:69]
	v_pk_mul_f32 v[66:67], v[82:83], v[66:67]
	v_pk_add_f32 v[82:83], v[156:157], 1.0 op_sel_hi:[1,0]
	v_pk_add_f32 v[84:85], v[158:159], 1.0 op_sel_hi:[1,0]
	v_rcp_f32_e32 v82, v82
	v_rcp_f32_e32 v84, v84
	v_rcp_f32_e32 v83, v83
	v_rcp_f32_e32 v85, v85
	v_mul_f32_e32 v152, v242, v242
	v_pk_mul_f32 v[68:69], v[68:69], v[152:153] op_sel_hi:[1,0]
	v_pk_mul_f32 v[66:67], v[66:67], v[152:153] op_sel_hi:[1,0]
	v_pk_mul_f32 v[68:69], v[68:69], v[82:83]
	v_pk_mul_f32 v[66:67], v[66:67], v[84:85]
	v_pk_mul_f32 v[82:83], v[4:5], v[154:155] op_sel_hi:[1,0]
	v_pk_mul_f32 v[84:85], v[2:3], v[154:155] op_sel_hi:[1,0]
	v_exp_f32_e32 v82, v82
	v_exp_f32_e32 v84, v84
	v_exp_f32_e32 v83, v83
	v_exp_f32_e32 v85, v85
	v_pk_mul_f32 v[4:5], v[20:21], v[4:5]
	v_pk_mul_f32 v[2:3], v[18:19], v[2:3]
	v_pk_add_f32 v[18:19], v[82:83], 1.0 op_sel_hi:[1,0]
	v_pk_add_f32 v[20:21], v[84:85], 1.0 op_sel_hi:[1,0]
	v_rcp_f32_e32 v18, v18
	v_rcp_f32_e32 v20, v20
	v_rcp_f32_e32 v19, v19
	v_rcp_f32_e32 v21, v21
	v_pk_mul_f32 v[4:5], v[4:5], v[152:153] op_sel_hi:[1,0]
	v_pk_mul_f32 v[2:3], v[2:3], v[152:153] op_sel_hi:[1,0]
	v_pk_mul_f32 v[18:19], v[4:5], v[18:19]
	v_pk_mul_f32 v[4:5], v[2:3], v[20:21]
	v_add_u32_e32 v20, s21, v141
	v_ashrrev_i32_e32 v21, 31, v20
	v_cvt_pk_bf16_f32 v2, v66, v67
	v_cvt_pk_bf16_f32 v3, v68, v69
	v_cvt_pk_bf16_f32 v4, v4, v5
	v_cvt_pk_bf16_f32 v5, v18, v19
	v_lshlrev_b64 v[18:19], 7, v[20:21]
	v_lshl_add_u64 v[18:19], s[28:29], 0, v[18:19]
	v_lshl_add_u64 v[18:19], v[18:19], 0, v[130:131]
	global_store_dwordx4 v[18:19], v[2:5], off
	ds_read_b128 v[66:69], v151
	ds_read_b128 v[2:5], v151
	ds_read_b128 v[82:85], v151
	ds_read_b128 v[18:21], v151
	v_mul_f32_e32 v154, 0xbfb8aa3b, v243
	v_pk_mul_f32 v[156:157], v[72:73], v[154:155] op_sel_hi:[1,0]
	v_pk_mul_f32 v[158:159], v[70:71], v[154:155] op_sel_hi:[1,0]
	v_exp_f32_e32 v156, v156
	v_exp_f32_e32 v158, v158
	v_exp_f32_e32 v157, v157
	v_exp_f32_e32 v159, v159
	v_pk_mul_f32 v[72:73], v[88:89], v[72:73]
	v_pk_mul_f32 v[70:71], v[86:87], v[70:71]
	v_pk_add_f32 v[86:87], v[156:157], 1.0 op_sel_hi:[1,0]
	v_pk_add_f32 v[88:89], v[158:159], 1.0 op_sel_hi:[1,0]
	v_rcp_f32_e32 v86, v86
	v_rcp_f32_e32 v88, v88
	v_rcp_f32_e32 v87, v87
	v_rcp_f32_e32 v89, v89
	v_mul_f32_e32 v152, v243, v243
	v_pk_mul_f32 v[72:73], v[72:73], v[152:153] op_sel_hi:[1,0]
	v_pk_mul_f32 v[70:71], v[70:71], v[152:153] op_sel_hi:[1,0]
	v_pk_mul_f32 v[72:73], v[72:73], v[86:87]
	v_pk_mul_f32 v[70:71], v[70:71], v[88:89]
	v_pk_mul_f32 v[86:87], v[8:9], v[154:155] op_sel_hi:[1,0]
	v_pk_mul_f32 v[88:89], v[6:7], v[154:155] op_sel_hi:[1,0]
	v_exp_f32_e32 v86, v86
	v_exp_f32_e32 v88, v88
	v_exp_f32_e32 v87, v87
	v_exp_f32_e32 v89, v89
	v_pk_mul_f32 v[8:9], v[24:25], v[8:9]
	v_pk_mul_f32 v[6:7], v[22:23], v[6:7]
	v_pk_add_f32 v[22:23], v[86:87], 1.0 op_sel_hi:[1,0]
	v_pk_add_f32 v[24:25], v[88:89], 1.0 op_sel_hi:[1,0]
	v_rcp_f32_e32 v22, v22
	v_rcp_f32_e32 v24, v24
	v_rcp_f32_e32 v23, v23
	v_rcp_f32_e32 v25, v25
	v_pk_mul_f32 v[8:9], v[8:9], v[152:153] op_sel_hi:[1,0]
	v_pk_mul_f32 v[6:7], v[6:7], v[152:153] op_sel_hi:[1,0]
	v_pk_mul_f32 v[22:23], v[8:9], v[22:23]
	v_pk_mul_f32 v[8:9], v[6:7], v[24:25]
	v_add_u32_e32 v24, s21, v142
	v_ashrrev_i32_e32 v25, 31, v24
	v_cvt_pk_bf16_f32 v6, v70, v71
	v_cvt_pk_bf16_f32 v7, v72, v73
	v_cvt_pk_bf16_f32 v8, v8, v9
	v_cvt_pk_bf16_f32 v9, v22, v23
	v_lshlrev_b64 v[22:23], 7, v[24:25]
	v_lshl_add_u64 v[22:23], s[28:29], 0, v[22:23]
	v_lshl_add_u64 v[22:23], v[22:23], 0, v[130:131]
	global_store_dwordx4 v[22:23], v[6:9], off
	ds_read_b128 v[70:73], v151
	ds_read_b128 v[6:9], v151
	ds_read_b128 v[86:89], v151
	ds_read_b128 v[22:25], v151
	v_mul_f32_e32 v154, 0xbfb8aa3b, v244
	v_pk_mul_f32 v[156:157], v[76:77], v[154:155] op_sel_hi:[1,0]
	v_pk_mul_f32 v[158:159], v[74:75], v[154:155] op_sel_hi:[1,0]
	v_exp_f32_e32 v156, v156
	v_exp_f32_e32 v158, v158
	v_exp_f32_e32 v157, v157
	v_exp_f32_e32 v159, v159
	v_pk_mul_f32 v[76:77], v[96:97], v[76:77]
	v_pk_mul_f32 v[74:75], v[94:95], v[74:75]
	v_pk_add_f32 v[94:95], v[156:157], 1.0 op_sel_hi:[1,0]
	v_pk_add_f32 v[96:97], v[158:159], 1.0 op_sel_hi:[1,0]
	v_rcp_f32_e32 v94, v94
	v_rcp_f32_e32 v96, v96
	v_rcp_f32_e32 v95, v95
	v_rcp_f32_e32 v97, v97
	v_mul_f32_e32 v152, v244, v244
	v_pk_mul_f32 v[76:77], v[76:77], v[152:153] op_sel_hi:[1,0]
	v_pk_mul_f32 v[74:75], v[74:75], v[152:153] op_sel_hi:[1,0]
	v_pk_mul_f32 v[76:77], v[76:77], v[94:95]
	v_pk_mul_f32 v[74:75], v[74:75], v[96:97]
	v_pk_mul_f32 v[94:95], v[12:13], v[154:155] op_sel_hi:[1,0]
	v_pk_mul_f32 v[96:97], v[10:11], v[154:155] op_sel_hi:[1,0]
	v_exp_f32_e32 v94, v94
	v_exp_f32_e32 v96, v96
	v_exp_f32_e32 v95, v95
	v_exp_f32_e32 v97, v97
	v_pk_mul_f32 v[12:13], v[32:33], v[12:13]
	v_pk_mul_f32 v[10:11], v[30:31], v[10:11]
	v_pk_add_f32 v[30:31], v[94:95], 1.0 op_sel_hi:[1,0]
	v_pk_add_f32 v[32:33], v[96:97], 1.0 op_sel_hi:[1,0]
	v_rcp_f32_e32 v30, v30
	v_rcp_f32_e32 v32, v32
	v_rcp_f32_e32 v31, v31
	v_rcp_f32_e32 v33, v33
	v_pk_mul_f32 v[12:13], v[12:13], v[152:153] op_sel_hi:[1,0]
	v_pk_mul_f32 v[10:11], v[10:11], v[152:153] op_sel_hi:[1,0]
	v_pk_mul_f32 v[30:31], v[12:13], v[30:31]
	v_pk_mul_f32 v[12:13], v[10:11], v[32:33]
	v_add_u32_e32 v32, s21, v143
	v_ashrrev_i32_e32 v33, 31, v32
	v_cvt_pk_bf16_f32 v10, v74, v75
	v_cvt_pk_bf16_f32 v11, v76, v77
	v_cvt_pk_bf16_f32 v12, v12, v13
	v_cvt_pk_bf16_f32 v13, v30, v31
	v_lshlrev_b64 v[30:31], 7, v[32:33]
	v_lshl_add_u64 v[30:31], s[28:29], 0, v[30:31]
	v_lshl_add_u64 v[30:31], v[30:31], 0, v[130:131]
	global_store_dwordx4 v[30:31], v[10:13], off
	ds_read_b128 v[74:77], v151
	ds_read_b128 v[10:13], v151
	ds_read_b128 v[94:97], v151
	ds_read_b128 v[30:33], v151
	v_mul_f32_e32 v154, 0xbfb8aa3b, v245
	v_pk_mul_f32 v[156:157], v[92:93], v[154:155] op_sel_hi:[1,0]
	v_pk_mul_f32 v[158:159], v[90:91], v[154:155] op_sel_hi:[1,0]
	v_exp_f32_e32 v156, v156
	v_exp_f32_e32 v158, v158
	v_exp_f32_e32 v157, v157
	v_exp_f32_e32 v159, v159
	v_pk_mul_f32 v[92:93], v[116:117], v[92:93]
	v_pk_mul_f32 v[90:91], v[114:115], v[90:91]
	v_pk_add_f32 v[114:115], v[156:157], 1.0 op_sel_hi:[1,0]
	v_pk_add_f32 v[116:117], v[158:159], 1.0 op_sel_hi:[1,0]
	v_rcp_f32_e32 v114, v114
	v_rcp_f32_e32 v116, v116
	v_rcp_f32_e32 v115, v115
	v_rcp_f32_e32 v117, v117
	v_mul_f32_e32 v152, v245, v245
	v_pk_mul_f32 v[92:93], v[92:93], v[152:153] op_sel_hi:[1,0]
	v_pk_mul_f32 v[90:91], v[90:91], v[152:153] op_sel_hi:[1,0]
	v_pk_mul_f32 v[92:93], v[92:93], v[114:115]
	v_pk_mul_f32 v[90:91], v[90:91], v[116:117]
	v_pk_mul_f32 v[114:115], v[28:29], v[154:155] op_sel_hi:[1,0]
	v_pk_mul_f32 v[116:117], v[26:27], v[154:155] op_sel_hi:[1,0]
	v_exp_f32_e32 v114, v114
	v_exp_f32_e32 v116, v116
	v_exp_f32_e32 v115, v115
	v_exp_f32_e32 v117, v117
	v_pk_mul_f32 v[28:29], v[52:53], v[28:29]
	v_pk_mul_f32 v[26:27], v[50:51], v[26:27]
	v_pk_add_f32 v[50:51], v[114:115], 1.0 op_sel_hi:[1,0]
	v_pk_add_f32 v[52:53], v[116:117], 1.0 op_sel_hi:[1,0]
	v_rcp_f32_e32 v50, v50
	v_rcp_f32_e32 v52, v52
	v_rcp_f32_e32 v51, v51
	v_rcp_f32_e32 v53, v53
	v_pk_mul_f32 v[28:29], v[28:29], v[152:153] op_sel_hi:[1,0]
	v_pk_mul_f32 v[26:27], v[26:27], v[152:153] op_sel_hi:[1,0]
	v_pk_mul_f32 v[50:51], v[28:29], v[50:51]
	v_pk_mul_f32 v[28:29], v[26:27], v[52:53]
	v_add_u32_e32 v52, s21, v144
	v_ashrrev_i32_e32 v53, 31, v52
	v_cvt_pk_bf16_f32 v26, v90, v91
	v_cvt_pk_bf16_f32 v27, v92, v93
	v_cvt_pk_bf16_f32 v28, v28, v29
	v_cvt_pk_bf16_f32 v29, v50, v51
	v_lshlrev_b64 v[50:51], 7, v[52:53]
	v_lshl_add_u64 v[50:51], s[28:29], 0, v[50:51]
	v_lshl_add_u64 v[50:51], v[50:51], 0, v[130:131]
	global_store_dwordx4 v[50:51], v[26:29], off
	ds_read_b128 v[90:93], v151
	ds_read_b128 v[26:29], v151
	ds_read_b128 v[114:117], v151
	ds_read_b128 v[50:53], v151
	v_mul_f32_e32 v154, 0xbfb8aa3b, v246
	v_pk_mul_f32 v[156:157], v[104:105], v[154:155] op_sel_hi:[1,0]
	v_pk_mul_f32 v[158:159], v[102:103], v[154:155] op_sel_hi:[1,0]
	v_exp_f32_e32 v156, v156
	v_exp_f32_e32 v158, v158
	v_exp_f32_e32 v157, v157
	v_exp_f32_e32 v159, v159
	v_pk_mul_f32 v[104:105], v[120:121], v[104:105]
	v_pk_mul_f32 v[102:103], v[118:119], v[102:103]
	v_pk_add_f32 v[118:119], v[156:157], 1.0 op_sel_hi:[1,0]
	v_pk_add_f32 v[120:121], v[158:159], 1.0 op_sel_hi:[1,0]
	v_rcp_f32_e32 v118, v118
	v_rcp_f32_e32 v120, v120
	v_rcp_f32_e32 v119, v119
	v_rcp_f32_e32 v121, v121
	v_mul_f32_e32 v152, v246, v246
	v_pk_mul_f32 v[104:105], v[104:105], v[152:153] op_sel_hi:[1,0]
	v_pk_mul_f32 v[102:103], v[102:103], v[152:153] op_sel_hi:[1,0]
	v_pk_mul_f32 v[104:105], v[104:105], v[118:119]
	v_pk_mul_f32 v[102:103], v[102:103], v[120:121]
	v_pk_mul_f32 v[118:119], v[40:41], v[154:155] op_sel_hi:[1,0]
	v_pk_mul_f32 v[120:121], v[38:39], v[154:155] op_sel_hi:[1,0]
	v_exp_f32_e32 v118, v118
	v_exp_f32_e32 v120, v120
	v_exp_f32_e32 v119, v119
	v_exp_f32_e32 v121, v121
	v_pk_mul_f32 v[40:41], v[56:57], v[40:41]
	v_pk_mul_f32 v[38:39], v[54:55], v[38:39]
	v_pk_add_f32 v[54:55], v[118:119], 1.0 op_sel_hi:[1,0]
	v_pk_add_f32 v[56:57], v[120:121], 1.0 op_sel_hi:[1,0]
	v_rcp_f32_e32 v54, v54
	v_rcp_f32_e32 v56, v56
	v_rcp_f32_e32 v55, v55
	v_rcp_f32_e32 v57, v57
	v_pk_mul_f32 v[40:41], v[40:41], v[152:153] op_sel_hi:[1,0]
	v_pk_mul_f32 v[38:39], v[38:39], v[152:153] op_sel_hi:[1,0]
	v_pk_mul_f32 v[54:55], v[40:41], v[54:55]
	v_pk_mul_f32 v[40:41], v[38:39], v[56:57]
	v_add_u32_e32 v56, s21, v145
	v_ashrrev_i32_e32 v57, 31, v56
	v_cvt_pk_bf16_f32 v38, v102, v103
	v_cvt_pk_bf16_f32 v39, v104, v105
	v_cvt_pk_bf16_f32 v40, v40, v41
	v_cvt_pk_bf16_f32 v41, v54, v55
	v_lshlrev_b64 v[54:55], 7, v[56:57]
	v_lshl_add_u64 v[54:55], s[28:29], 0, v[54:55]
	v_lshl_add_u64 v[54:55], v[54:55], 0, v[130:131]
	global_store_dwordx4 v[54:55], v[38:41], off
	ds_read_b128 v[102:105], v151
	ds_read_b128 v[38:41], v151
	ds_read_b128 v[118:121], v151
	ds_read_b128 v[54:57], v151
	v_mul_f32_e32 v154, 0xbfb8aa3b, v247
	v_pk_mul_f32 v[156:157], v[108:109], v[154:155] op_sel_hi:[1,0]
	v_pk_mul_f32 v[158:159], v[106:107], v[154:155] op_sel_hi:[1,0]
	v_exp_f32_e32 v156, v156
	v_exp_f32_e32 v158, v158
	v_exp_f32_e32 v157, v157
	v_exp_f32_e32 v159, v159
	v_pk_mul_f32 v[108:109], v[124:125], v[108:109]
	v_pk_mul_f32 v[106:107], v[122:123], v[106:107]
	v_pk_add_f32 v[122:123], v[156:157], 1.0 op_sel_hi:[1,0]
	v_pk_add_f32 v[124:125], v[158:159], 1.0 op_sel_hi:[1,0]
	v_rcp_f32_e32 v122, v122
	v_rcp_f32_e32 v124, v124
	v_rcp_f32_e32 v123, v123
	v_rcp_f32_e32 v125, v125
	v_mul_f32_e32 v152, v247, v247
	v_pk_mul_f32 v[108:109], v[108:109], v[152:153] op_sel_hi:[1,0]
	v_pk_mul_f32 v[106:107], v[106:107], v[152:153] op_sel_hi:[1,0]
	v_pk_mul_f32 v[108:109], v[108:109], v[122:123]
	v_pk_mul_f32 v[106:107], v[106:107], v[124:125]
	v_pk_mul_f32 v[122:123], v[44:45], v[154:155] op_sel_hi:[1,0]
	v_pk_mul_f32 v[124:125], v[42:43], v[154:155] op_sel_hi:[1,0]
	v_exp_f32_e32 v122, v122
	v_exp_f32_e32 v124, v124
	v_exp_f32_e32 v123, v123
	v_exp_f32_e32 v125, v125
	v_pk_mul_f32 v[44:45], v[60:61], v[44:45]
	v_pk_mul_f32 v[42:43], v[58:59], v[42:43]
	v_pk_add_f32 v[58:59], v[122:123], 1.0 op_sel_hi:[1,0]
	v_pk_add_f32 v[60:61], v[124:125], 1.0 op_sel_hi:[1,0]
	v_rcp_f32_e32 v58, v58
	v_rcp_f32_e32 v60, v60
	v_rcp_f32_e32 v59, v59
	v_rcp_f32_e32 v61, v61
	v_pk_mul_f32 v[44:45], v[44:45], v[152:153] op_sel_hi:[1,0]
	v_pk_mul_f32 v[42:43], v[42:43], v[152:153] op_sel_hi:[1,0]
	v_pk_mul_f32 v[58:59], v[44:45], v[58:59]
	v_pk_mul_f32 v[44:45], v[42:43], v[60:61]
	v_add_u32_e32 v60, s21, v146
	v_ashrrev_i32_e32 v61, 31, v60
	v_cvt_pk_bf16_f32 v42, v106, v107
	v_cvt_pk_bf16_f32 v43, v108, v109
	v_cvt_pk_bf16_f32 v44, v44, v45
	v_cvt_pk_bf16_f32 v45, v58, v59
	v_lshlrev_b64 v[58:59], 7, v[60:61]
	v_lshl_add_u64 v[58:59], s[28:29], 0, v[58:59]
	v_lshl_add_u64 v[58:59], v[58:59], 0, v[130:131]
	global_store_dwordx4 v[58:59], v[42:45], off
	ds_read_b128 v[106:109], v151
	ds_read_b128 v[42:45], v151
	ds_read_b128 v[122:125], v151
	ds_read_b128 v[58:61], v151
	v_mul_f32_e32 v150, v248, v248
	v_mul_f32_e32 v152, 0xbfb8aa3b, v248
	v_pk_mul_f32 v[154:155], v[112:113], v[152:153] op_sel_hi:[1,0]
	v_pk_mul_f32 v[156:157], v[110:111], v[152:153] op_sel_hi:[1,0]
	v_exp_f32_e32 v154, v154
	v_exp_f32_e32 v156, v156
	v_exp_f32_e32 v155, v155
	v_exp_f32_e32 v157, v157
	v_pk_mul_f32 v[112:113], v[128:129], v[112:113]
	v_pk_mul_f32 v[110:111], v[126:127], v[110:111]
	v_pk_add_f32 v[126:127], v[154:155], 1.0 op_sel_hi:[1,0]
	v_pk_add_f32 v[128:129], v[156:157], 1.0 op_sel_hi:[1,0]
	v_rcp_f32_e32 v126, v126
	v_rcp_f32_e32 v128, v128
	v_rcp_f32_e32 v127, v127
	v_rcp_f32_e32 v129, v129
	v_pk_mul_f32 v[112:113], v[112:113], v[150:151] op_sel_hi:[1,0]
	v_pk_mul_f32 v[110:111], v[110:111], v[150:151] op_sel_hi:[1,0]
	v_pk_mul_f32 v[112:113], v[112:113], v[126:127]
	v_pk_mul_f32 v[110:111], v[110:111], v[128:129]
	v_pk_mul_f32 v[126:127], v[48:49], v[152:153] op_sel_hi:[1,0]
	v_pk_mul_f32 v[128:129], v[46:47], v[152:153] op_sel_hi:[1,0]
	v_exp_f32_e32 v126, v126
	v_exp_f32_e32 v128, v128
	v_exp_f32_e32 v127, v127
	v_exp_f32_e32 v129, v129
	v_pk_mul_f32 v[48:49], v[64:65], v[48:49]
	v_pk_mul_f32 v[46:47], v[62:63], v[46:47]
	v_pk_add_f32 v[62:63], v[126:127], 1.0 op_sel_hi:[1,0]
	v_pk_add_f32 v[64:65], v[128:129], 1.0 op_sel_hi:[1,0]
	v_rcp_f32_e32 v62, v62
	v_rcp_f32_e32 v64, v64
	v_rcp_f32_e32 v63, v63
	v_rcp_f32_e32 v65, v65
	v_pk_mul_f32 v[48:49], v[48:49], v[150:151] op_sel_hi:[1,0]
	v_pk_mul_f32 v[46:47], v[46:47], v[150:151] op_sel_hi:[1,0]
	v_pk_mul_f32 v[62:63], v[48:49], v[62:63]
	v_pk_mul_f32 v[48:49], v[46:47], v[64:65]
	v_add_u32_e32 v64, s21, v147
	v_ashrrev_i32_e32 v65, 31, v64
	v_cvt_pk_bf16_f32 v46, v110, v111
	v_cvt_pk_bf16_f32 v47, v112, v113
	v_cvt_pk_bf16_f32 v48, v48, v49
	v_cvt_pk_bf16_f32 v49, v62, v63
	v_lshlrev_b64 v[62:63], 7, v[64:65]
	v_lshl_add_u64 v[62:63], s[28:29], 0, v[62:63]
	v_lshl_add_u64 v[62:63], v[62:63], 0, v[130:131]
	global_store_dwordx4 v[62:63], v[46:49], off
	ds_read_b128 v[110:113], v151
	ds_read_b128 v[46:49], v151
	ds_read_b128 v[126:129], v151
	ds_read_b128 v[62:65], v151
	s_cbranch_vccnz .LBB0_867
	s_andn2_b64 vcc, exec, s[2:3]
	s_cbranch_vccnz .LBB0_866
	s_barrier
	s_branch .LBB0_866
